# P3: workgroups 0-31 run their prompt compression tile first, decode tiles after (tail overlap)
# speedup vs baseline: 1.0162x; 1.0047x over previous
; #define LAS __attribute__((address_space(3)))
; __global__ void __launch_bounds__(NWAVES * 64, 2) fwd_kernel(Params P) {
;     extern __shared__ __attribute__((aligned(16))) unsigned char lds_raw[];
;     Ctx C;
;     C.lds = (LAS unsigned char*)lds_raw;
;     C.wave = __builtin_amdgcn_readfirstlane(threadIdx.x >> 6);
;     C.nblk = gridDim.x; C.blk = blockIdx.x;
;     volatile LAS unsigned* MISC = (volatile LAS unsigned*)(C.lds + MISC_OFF);
;     for (int u = threadIdx.x; u < (LDS_BYTES - LDSCTL_OFF) / 4; u += NWAVES * 64) ((LAS unsigned*)(C.lds + LDSCTL_OFF))[u] = 0u;
;     __syncthreads();
;     unsigned* ctl = (unsigned*)(P.ws + WS_CTL);
;     XcdBarrier bar = xcd_barrier_post(ctl + CW_BAR + P.li * XCD_BAR_WORDS, MISC + 8);
_Z10fwd_kernel6Params:
	s_mov_b32 s101, 0
	s_mov_b64 s[90:91], s[0:1]
	v_readfirstlane_b32 s0, v0
	s_load_dword s68, s[90:91], 0x120
	v_lshl_add_u32 v2, v0, 2, 0
	v_writelane_b32 v254, s0, 0
	s_add_u32 s0, s90, 0x120
	s_addc_u32 s1, s91, 0
	v_writelane_b32 v254, s0, 1
	s_mov_b32 s87, s2
	v_or_b32_e32 v1, 0xfffffe00, v0
	v_writelane_b32 v254, s1, 2
	v_add_u32_e32 v2, 0x20000, v2
	s_mov_b64 s[2:3], 0
	v_mov_b32_e32 v3, 0
	s_movk_i32 s0, 0x1dff

; template <class Epi, class Sched, bool ALIGN_EPI = false, bool SP2 = false>
; __device__ __forceinline__ void gemm_phase(PG8_LAS unsigned char* lds, const Gemm g, const Sched& S, const Epi& E, int wave_sgpr) {
;     int tid_ = wave_sgpr * 64 + fresh_lane();
;     const int tid = tid_, wid = __builtin_amdgcn_readfirstlane(tid >> 6), lane = tid & 63, wr = wid >> 2, wc = wid & 3, fr = lane & 15, fq = lane >> 4;
;     const int K = g.K, nt = K / BK;
;     unsigned voffA[2], voffB[2];
; #pragma unroll
;     for (int i = 0; i < 2; ++i) { int R, C; stage_rc(tid * 16 + i * 8192, R, C); const int Rb = Epi::PERM ? ((R & ~31) + perm32(R & 31)) : R;
;         voffA[i] = (unsigned)(R * g.lda + C) * 2u; voffB[i] = (unsigned)(Rb * g.ldb + C) * 2u; }
;     const size_t kstep = (size_t)(BK * 2);
;     const size_t hstepA = (size_t)HALF * g.lda * 2, hstepB = (size_t)HALF * g.ldb * 2;
;     const unsigned ldsw = (unsigned)wid * 1024u;
;     const int aoff = lds_byte(wr * 64 + fr, fq * 8), boff = lds_byte(wc * 32 + fr, fq * 8);
;     ...
;     Unit cur, nxt; int ui = 0;
;     if (!S.next(0, cur)) return;
;     f32x4 acc[2][2][4][2];
; #pragma unroll
;     for (int a = 0; a < 2; ++a)
; #pragma unroll
;         for (int b = 0; b < 2; ++b)
; #pragma unroll
;             for (int m = 0; m < 4; ++m)
; #pragma unroll
;                 for (int n = 0; n < 2; ++n) acc[a][b][m][n] = (f32x4){0.f, 0.f, 0.f, 0.f};
;     bf16x8 At[4][2], B0[2][2], B1[2][2];
;     const char* cA = S.abase(g, cur); const char* cB = S.bbase(g, cur);
;     S.a_ready(cur);
;     if constexpr (SP2) {
;         PG8_STAGE(PG8_SB(0, 0), cB, voffB); PG8_STAGE(PG8_SB(0, 1), cB + hstepB, voffB); PG8_STAGE(PG8_SA(0, 0), cA, voffA); PG8_STAGE(PG8_SA(0, 1), cA + hstepA, voffA);
;         if (wr == 1) PG8_BAR;
;         PG8_WAIT_V(2); PG8_BAR;
;         PG8_STAGE(PG8_SB(1, 0), cB + kstep, voffB); PG8_STAGE(PG8_SA(1, 0), cA + kstep, voffA); PG8_STAGE(PG8_SB(1, 1), cB + hstepB + kstep, voffB);
;         PG8_WAIT_V(6); PG8_BAR;
;     } else {
;         PG8_STAGE(PG8_SB(0, 0), cB, voffB); PG8_STAGE(PG8_SA(0, 0), cA, voffA); PG8_STAGE(PG8_SB(0, 1), cB + hstepB, voffB); PG8_STAGE(PG8_SA(0, 1), cA + hstepA, voffA);
;         if (wr == 1) PG8_BAR;
;         PG8_WAIT_V(4); PG8_BAR;
;         PG8_STAGE(PG8_SB(1, 0), cB + kstep, voffB); PG8_STAGE(PG8_SA(1, 0), cA + kstep, voffA); PG8_STAGE(PG8_SB(1, 1), cB + hstepB + kstep, voffB);
.LBB0_1065:
	v_readlane_b32 s0, v254, 8
	v_readlane_b32 s1, v254, 9
	s_cmp_lt_i32 s0, 4
	s_cselect_b64 s[0:1], -1, 0
	s_and_b64 s[8:9], s[0:1], s[2:3]
	s_andn2_b64 vcc, exec, s[8:9]
	s_cbranch_vccnz .LBB0_1136
	s_load_dwordx2 s[2:3], s[90:91], 0x108
	s_waitcnt lgkmcnt(0)
	s_add_u32 s1, s2, 0xc000000
	s_addc_u32 s30, s3, 0
	s_add_u32 s31, s2, 0x1b00000
	s_addc_u32 s33, s3, 0
	s_add_u32 s34, s2, 0x32800000
	s_addc_u32 s35, s3, 0
	s_add_u32 s36, s2, 0x34b00000
	s_addc_u32 s37, s3, 0
	s_add_u32 s38, s2, 0x1d80000
	v_readlane_b32 s0, v254, 0
	s_addc_u32 s39, s3, 0
	s_andn2_b32 s0, s0, 63
	s_bitcmp1_b32 s101, 4
	s_cbranch_scc1 .Lmy_d
	s_cmpk_lg_i32 s68, 0x100
	s_cbranch_scc1 .Lmy_d
	s_cmpk_gt_u32 s87, 31
	s_cbranch_scc1 .Lmy_d
	s_bitset1_b32 s101, 4
	s_branch .LBB0_1089
.Lmy_d:
	s_cmpk_lt_i32 s87, 0x200
	s_cselect_b64 s[4:5], -1, 0
	s_and_b32 s2, s87, 0xff
	v_mbcnt_lo_u32_b32 v8, -1, 0
	v_mbcnt_hi_u32_b32 v8, -1, v8
	s_add_i32 s28, s2, 16
	v_add_u32_e32 v0, s0, v8
	s_ashr_i32 s2, s87, 8
	s_cmpk_gt_i32 s87, 0x1ff
	v_readfirstlane_b32 s6, v0
	s_cbranch_scc1 .LBB0_1084
	v_lshlrev_b32_e32 v1, 4, v0
	v_add_u32_e32 v2, 0x2000, v1
	v_ashrrev_i32_e32 v3, 31, v2
	v_lshrrev_b32_e32 v3, 22, v3
	v_add_u32_e32 v3, v2, v3
	v_ashrrev_i32_e32 v9, 10, v3
	v_mul_i32_i24_e32 v3, 0x400, v9
	v_sub_u32_e32 v2, v2, v3
	v_lshrrev_b32_e32 v3, 4, v2
	v_bitop3_b32 v2, v3, v2, 32 bitop3:0x6c
	v_ashrrev_i32_e32 v3, 31, v2
	v_lshrrev_b32_e32 v3, 26, v3
	v_add_u32_e32 v3, v2, v3
	v_lshlrev_b32_e32 v4, 3, v9
	v_ashrrev_i32_e32 v10, 6, v3
	v_and_b32_e32 v4, -16, v4
	v_add_u32_e32 v4, v10, v4
	v_and_b32_e32 v5, 3, v10
	s_mov_b32 s3, 0xfffe0
	v_lshrrev_b32_e32 v6, 2, v4
	v_lshlrev_b32_e32 v7, 1, v4
	v_and_b32_e32 v3, 0xc0, v3
	v_and_or_b32 v5, v4, s3, v5
	v_and_b32_e32 v6, 4, v6
	v_and_b32_e32 v7, 24, v7
	v_sub_u32_e32 v2, v2, v3
	v_mov_b32_e32 v3, 1
	v_or3_b32 v5, v5, v6, v7
	v_lshlrev_b32_e32 v6, 5, v9
	v_ashrrev_i16_sdwa v2, v3, sext(v2) dst_sel:DWORD dst_unused:UNUSED_PAD src0_sel:DWORD src1_sel:BYTE_0
	v_and_b32_e32 v6, 32, v6
	v_bfe_i32 v11, v2, 0, 16
	v_add_lshl_u32 v2, v6, v11, 1
	v_lshl_add_u32 v144, v5, 12, v2
	v_lshl_add_u32 v146, v4, 11, v2
	v_bfe_i32 v2, v0, 27, 1
	v_lshrrev_b32_e32 v2, 22, v2
	v_add_u32_e32 v2, v1, v2
	v_and_b32_e32 v2, 0xfffffc00, v2
	v_sub_u32_e32 v1, v1, v2
	v_lshrrev_b32_e32 v2, 4, v1
	v_ashrrev_i32_e32 v4, 31, v0
	v_bitop3_b32 v1, v2, v1, 32 bitop3:0x6c
	v_lshrrev_b32_e32 v4, 26, v4
	v_ashrrev_i32_e32 v2, 31, v1
	v_add_u32_e32 v0, v0, v4
	v_lshrrev_b32_e32 v2, 26, v2
	v_ashrrev_i32_e32 v13, 6, v0
	v_add_u32_e32 v2, v1, v2
	v_lshlrev_b32_e32 v0, 3, v13
	v_ashrrev_i32_e32 v12, 6, v2
	v_and_b32_e32 v0, -16, v0
	v_add_u32_e32 v0, v12, v0
	v_and_b32_e32 v4, 3, v12
	v_lshrrev_b32_e32 v5, 2, v0
	v_lshlrev_b32_e32 v6, 1, v0
	v_and_b32_e32 v2, 0xc0, v2
	s_ashr_i32 s12, s6, 6
	v_and_or_b32 v4, v0, s3, v4
	v_and_b32_e32 v5, 4, v5
	v_and_b32_e32 v6, 24, v6
	v_sub_u32_e32 v1, v1, v2
	s_ashr_i32 s3, s2, 31
	s_ashr_i32 s13, s6, 8
	s_lshl_b32 s29, s12, 10
	v_or3_b32 v4, v4, v5, v6
	v_lshlrev_b32_e32 v5, 5, v13
	v_ashrrev_i16_sdwa v1, v3, sext(v1) dst_sel:DWORD dst_unused:UNUSED_PAD src0_sel:DWORD src1_sel:BYTE_0
	s_lshl_b32 s15, s28, 19
	s_lshl_b64 s[10:11], s[2:3], 20
	v_and_b32_e32 v5, 32, v5
	v_bfe_i32 v14, v1, 0, 16
	s_add_u32 s24, s31, s10
	v_add_lshl_u32 v1, v5, v14, 1
	s_addc_u32 s25, s33, s11
	s_add_i32 s3, s29, 0
	v_lshl_add_u32 v148, v4, 12, v1
	s_add_i32 m0, s3, 0x10000
	s_mul_i32 s14, s2, 0x8a00000
	global_load_lds_dwordx4 v148, s[24:25]
	s_add_i32 m0, s3, 0x12000
	s_mul_hi_i32 s7, s2, 0x8a00000
	s_add_u32 s14, s1, s14
	s_addc_u32 s7, s30, s7
	s_add_u32 s10, s24, 0x80000
	global_load_lds_dwordx4 v144, s[24:25]
	s_addc_u32 s11, s25, 0
	s_add_i32 m0, s3, 0x14000
	v_lshl_add_u32 v150, v0, 11, v1
	global_load_lds_dwordx4 v148, s[10:11]
	s_add_i32 m0, s3, 0x16000
	s_add_u32 s22, s14, s15
	s_addc_u32 s23, s7, 0
	s_add_i32 s40, s3, 0x2000
	global_load_lds_dwordx4 v144, s[10:11]
	s_mov_b32 m0, s3
	s_add_u32 s10, s22, 0x40000
	global_load_lds_dwordx4 v150, s[22:23]
	s_mov_b32 m0, s40
	s_addc_u32 s11, s23, 0
	s_add_i32 s41, s3, 0x4000
	global_load_lds_dwordx4 v146, s[22:23]
	s_mov_b32 m0, s41
	s_add_i32 s42, s3, 0x6000
	global_load_lds_dwordx4 v150, s[10:11]
	s_mov_b32 m0, s42
	v_mov_b32_e32 v149, 0
	global_load_lds_dwordx4 v146, s[10:11]
	v_mov_b32_e32 v145, v149
	v_mov_b32_e32 v151, v149
	v_mov_b32_e32 v147, v149
	s_cmp_eq_u32 s13, 1
	s_mov_b32 s7, 0
	v_lshl_add_u64 v[6:7], s[24:25], 0, v[148:149]
	v_lshl_add_u64 v[4:5], s[24:25], 0, v[144:145]
	v_lshl_add_u64 v[0:1], s[22:23], 0, v[150:151]
	s_cselect_b64 s[10:11], -1, 0
	s_cmp_lg_u32 s13, 1
	v_lshl_add_u64 v[2:3], s[22:23], 0, v[146:147]
	s_cbranch_scc1 .LBB0_1069
	s_barrier

.LBB0_1089:
	s_and_b32 s99, s101, 0x30
	s_cmpk_eq_u32 s99, 0x30
	s_cbranch_scc1 .LBB0_1136
	s_cmp_gt_i32 s68, 63
	s_cselect_b64 s[4:5], -1, 0
	s_cmp_lt_i32 s68, 64
	s_cselect_b64 s[2:3], -1, 0
	s_cmp_lt_i32 s87, 32
	s_cselect_b64 s[6:7], -1, 0
	s_or_b64 s[2:3], s[6:7], s[2:3]
	s_and_b64 vcc, exec, s[2:3]
	s_barrier
	s_cbranch_vccnz .LBB0_1092
	s_mov_b64 s[2:3], -1
	s_and_b64 vcc, exec, s[4:5]
	s_cbranch_vccnz .LBB0_1116

.LBB0_1116:
	s_and_b32 s99, s101, 0x30
	s_cmpk_eq_u32 s99, 0x10
	s_cbranch_scc0 .Lmy_t
	s_bitset1_b32 s101, 5
	s_mov_b64 s[2:3], -1
	s_branch .LBB0_1065
